# GEMM LDS staging layout: each LDS-DMA fetches whole 128B lines (8 rows x 64 cols, xor-swizzled), on top of LN residual + band epilogue rewrites
# speedup vs baseline: 1.0027x; 1.0027x over previous
.LBB0_50:
	s_andn2_b64 vcc, exec, s[0:1]
	s_cbranch_vccnz .LBB0_341
	v_readlane_b32 s0, v238, 4
	v_mov_b32_e32 v160, v204
	v_readlane_b32 s1, v238, 5
	s_andn2_b64 vcc, exec, s[0:1]
	v_readfirstlane_b32 s2, v160
	s_cbranch_vccnz .LBB0_341
	v_lshlrev_b32_e32 v0, 4, v160
	v_add_u32_e32 v3, 0x2000, v0
	v_ashrrev_i32_e32 v2, 31, v3
	v_lshrrev_b32_e32 v2, 22, v2
	v_add_u32_e32 v2, v3, v2
	v_ashrrev_i32_e32 v2, 10, v2
	v_lshlrev_b32_e32 v4, 5, v2
	v_and_b32_e32 v5, 32, v4
	v_mul_i32_i24_e32 v4, 0x400, v2
	v_sub_u32_e32 v3, v3, v4
	v_lshrrev_b32_e32 v4, 4, v3
	v_bitop3_b32 v4, v4, v3, 32 bitop3:0x6c
	v_ashrrev_i32_e32 v3, 31, v4
	v_lshrrev_b32_e32 v3, 26, v3
	v_add_u32_e32 v6, v4, v3
	v_ashrrev_i32_e32 v3, 6, v6
	v_and_b32_e32 v6, 0xc0, v6
	v_sub_u32_e32 v4, v4, v6
	v_ashrrev_i16_sdwa v4, v205, sext(v4) dst_sel:DWORD dst_unused:UNUSED_PAD src0_sel:DWORD src1_sel:BYTE_0
	v_lshlrev_b32_e32 v6, 3, v2
	v_bfe_i32 v4, v4, 0, 16
	v_and_b32_e32 v6, 0xffff0, v6
	v_add_u32_e32 v5, v5, v4
	v_add_lshl_u32 v6, v3, v6, 12
	v_lshl_add_u32 v130, v5, 1, v6
	v_ashrrev_i32_e32 v5, 31, v160
	v_lshrrev_b32_e32 v5, 26, v5
	v_add_u32_e32 v5, v160, v5
	v_ashrrev_i32_e32 v5, 6, v5
	v_lshlrev_b32_e32 v6, 5, v5
	v_and_b32_e32 v8, 32, v6
	v_bfe_i32 v6, v160, 27, 1
	v_lshrrev_b32_e32 v6, 22, v6
	v_add_u32_e32 v6, v0, v6
	v_and_b32_e32 v6, 0xfffffc00, v6
	v_sub_u32_e32 v0, v0, v6
	v_lshrrev_b32_e32 v6, 4, v0
	v_bitop3_b32 v0, v6, v0, 32 bitop3:0x6c
	v_ashrrev_i32_e32 v6, 31, v0
	v_lshrrev_b32_e32 v6, 26, v6
	v_add_u32_e32 v7, v0, v6
	v_ashrrev_i32_e32 v6, 6, v7
	v_and_b32_e32 v7, 0xc0, v7
	v_sub_u32_e32 v0, v0, v7
	v_ashrrev_i16_sdwa v0, v205, sext(v0) dst_sel:DWORD dst_unused:UNUSED_PAD src0_sel:DWORD src1_sel:BYTE_0
	s_ashr_i32 s1, s2, 6
	v_bfe_i32 v7, v0, 0, 16
	s_ashr_i32 s54, s2, 8
	s_lshl_b32 s80, s1, 10
	v_add_u32_e32 v0, v8, v7
	v_lshlrev_b32_e32 v8, 3, v5
	v_readlane_b32 s6, v237, 50
	v_and_b32_e32 v8, 0xffff0, v8
	v_readlane_b32 s7, v237, 51
	s_add_u32 s50, s78, s6
	v_add_lshl_u32 v8, v6, v8, 12
	s_addc_u32 s51, s79, s7
	s_add_i32 s82, s80, 0
	v_lshl_add_u32 v0, v0, 1, v8
	s_add_i32 m0, s82, 0x10000
	v_readlane_b32 s6, v236, 1
	v_and_b32_e32 v244, 63, v204
	v_lshrrev_b32_e32 v245, 6, v204
	v_lshrrev_b32_e32 v246, 3, v244
	v_and_b32_e32 v247, 7, v244
	v_xor_b32_e32 v247, v247, v246
	v_lshlrev_b32_e32 v247, 4, v247
	v_lshl_add_u32 v248, v245, 3, v246
	v_lshl_add_u32 v0, v248, 12, v247
	v_add_u32_e32 v130, 0x40000, v0
	global_load_lds_dwordx4 v0, s[50:51]
	s_add_i32 m0, s82, 0x12000
	s_add_u32 s14, s50, 0x80000
	global_load_lds_dwordx4 v130, s[50:51]
	s_addc_u32 s15, s51, 0
	s_add_i32 m0, s82, 0x14000
	v_readlane_b32 s7, v236, 2
	global_load_lds_dwordx4 v0, s[14:15]
	s_add_i32 m0, s82, 0x16000
	s_add_u32 s42, s56, s6
	s_addc_u32 s43, s57, s7
	s_add_i32 s83, s82, 0x2000
	global_load_lds_dwordx4 v130, s[14:15]
	s_mov_b32 m0, s82
	s_add_u32 s14, s42, 0x80000
	s_mov_b64 s[72:73], s[84:85]
	global_load_lds_dwordx4 v0, s[42:43]
	s_mov_b32 m0, s83
	s_addc_u32 s15, s43, 0
	s_add_i32 s84, s82, 0x4000
	global_load_lds_dwordx4 v130, s[42:43]
	s_mov_b32 m0, s84
	s_add_i32 s85, s82, 0x6000
	global_load_lds_dwordx4 v0, s[14:15]
	s_mov_b32 m0, s85
	s_mov_b32 s31, s29
	global_load_lds_dwordx4 v130, s[14:15]
	s_mov_b32 s75, s87
	s_cmp_lg_u32 s54, 1
	s_cbranch_scc1 .LBB0_54
	s_barrier
.LBB0_54:
	v_lshl_add_u64 v[8:9], s[50:51], 0, v[0:1]
	v_mov_b32_e32 v131, v1
	v_and_b32_e32 v161, 15, v160
	v_and_b32_e32 v16, 48, v160
	v_lshlrev_b32_e32 v17, 2, v160
	v_lshl_add_u64 v[10:11], s[50:51], 0, v[130:131]
	s_and_b32 s29, s1, 3
	s_lshl_b32 s0, s54, 13
	v_lshl_or_b32 v16, v161, 6, v16
	v_and_b32_e32 v17, 32, v17
	s_add_i32 m0, s82, 0x18000
	v_lshl_add_u64 v[8:9], v[8:9], 0, s[20:21]
	v_lshl_add_u64 v[12:13], s[42:43], 0, v[0:1]
	s_lshl_b32 s81, s54, 6
	v_bitop3_b32 v18, v16, s0, v17 bitop3:0xde
	s_lshl_b32 s0, s29, 12
	s_waitcnt vmcnt(2)
	s_barrier
	global_load_lds_dwordx4 v[8:9], off
	v_lshl_add_u64 v[8:9], v[10:11], 0, s[20:21]
	s_add_i32 m0, s82, 0x1a000
	s_add_i32 s14, s82, 0x8000
	s_add_i32 s15, s82, 0xa000
	v_lshl_add_u64 v[14:15], s[42:43], 0, v[130:131]
	global_load_lds_dwordx4 v[8:9], off
	v_lshl_add_u64 v[8:9], v[12:13], 0, s[20:21]
	s_mov_b32 m0, s14
	s_add_u32 s18, s50, 0x80080
	global_load_lds_dwordx4 v[8:9], off
	v_lshl_add_u64 v[8:9], v[14:15], 0, s[20:21]
	s_mov_b32 m0, s15
	s_addc_u32 s19, s51, 0
	global_load_lds_dwordx4 v[8:9], off
	s_add_i32 m0, s82, 0x1c000
	v_lshl_add_u64 v[8:9], s[18:19], 0, v[0:1]
	global_load_lds_dwordx4 v[8:9], off
	v_lshl_add_u64 v[8:9], s[18:19], 0, v[130:131]
	s_add_i32 m0, s82, 0x1e000
	v_mov_b32_e32 v50, 0
	global_load_lds_dwordx4 v[8:9], off
	v_lshlrev_b32_e32 v8, 15, v2
	v_and_b32_e32 v8, 0xffff0000, v8
	v_lshl_add_u32 v3, v3, 12, v8
	v_and_b32_e32 v2, 1, v2
	v_lshl_or_b32 v2, v2, 6, v3
	v_lshl_add_u32 v132, v4, 1, v2
	v_lshlrev_b32_e32 v2, 15, v5
	v_and_b32_e32 v2, 0xffff0000, v2
	s_waitcnt vmcnt(6)
	v_lshl_add_u32 v2, v6, 12, v2
	v_and_b32_e32 v3, 1, v5
	v_lshl_or_b32 v2, v3, 6, v2
	v_readlane_b32 s6, v237, 63
	v_or_b32_e32 v168, s81, v161
	v_bitop3_b32 v140, v16, s0, v17 bitop3:0xde
	v_mov_b32_e32 v133, v1
	v_lshl_add_u32 v134, v7, 1, v2
	v_mov_b32_e32 v135, v1
	s_mov_b32 s25, 0
	v_add_u32_e32 v141, 0, v18
	v_readlane_b32 s0, v237, 49
	s_mov_b32 s55, s6
	v_mov_b32_e32 v51, v50
	v_mov_b32_e32 v52, v50
	v_mov_b32_e32 v53, v50
	v_mov_b32_e32 v58, v50
	v_mov_b32_e32 v59, v50
	v_mov_b32_e32 v60, v50
	v_mov_b32_e32 v61, v50
	v_mov_b32_e32 v54, v50
	v_mov_b32_e32 v55, v50
	v_mov_b32_e32 v56, v50
	v_mov_b32_e32 v57, v50
	v_mov_b32_e32 v62, v50
	v_mov_b32_e32 v63, v50
	v_mov_b32_e32 v64, v50
	v_mov_b32_e32 v65, v50
	v_mov_b32_e32 v42, v50
	v_mov_b32_e32 v43, v50
	v_mov_b32_e32 v44, v50
	v_mov_b32_e32 v45, v50
	v_mov_b32_e32 v46, v50
	v_mov_b32_e32 v47, v50
	v_mov_b32_e32 v48, v50
	v_mov_b32_e32 v49, v50
	v_mov_b32_e32 v34, v50
	v_mov_b32_e32 v35, v50
	v_mov_b32_e32 v36, v50
	v_mov_b32_e32 v37, v50
	v_mov_b32_e32 v38, v50
	v_mov_b32_e32 v39, v50
	v_mov_b32_e32 v40, v50
	v_mov_b32_e32 v41, v50
	v_mov_b32_e32 v66, v50
	v_mov_b32_e32 v67, v50
	v_mov_b32_e32 v68, v50
	v_mov_b32_e32 v69, v50
	v_mov_b32_e32 v70, v50
	v_mov_b32_e32 v71, v50
	v_mov_b32_e32 v72, v50
	v_mov_b32_e32 v73, v50
	v_mov_b32_e32 v82, v50
	v_mov_b32_e32 v83, v50
	v_mov_b32_e32 v84, v50
	v_mov_b32_e32 v85, v50
	v_mov_b32_e32 v86, v50
	v_mov_b32_e32 v87, v50
	v_mov_b32_e32 v88, v50
	v_mov_b32_e32 v89, v50
	v_mov_b32_e32 v110, v50
	v_mov_b32_e32 v111, v50
	v_mov_b32_e32 v112, v50
	v_mov_b32_e32 v113, v50
	v_mov_b32_e32 v114, v50
	v_mov_b32_e32 v115, v50
	v_mov_b32_e32 v116, v50
	v_mov_b32_e32 v117, v50
	v_mov_b32_e32 v122, v50
	v_mov_b32_e32 v123, v50
	v_mov_b32_e32 v124, v50
	v_mov_b32_e32 v125, v50
	v_mov_b32_e32 v126, v50
	v_mov_b32_e32 v127, v50
	v_mov_b32_e32 v128, v50
	v_mov_b32_e32 v129, v50
	v_mov_b32_e32 v26, v50
	v_mov_b32_e32 v27, v50
	v_mov_b32_e32 v28, v50
	v_mov_b32_e32 v29, v50
	v_mov_b32_e32 v30, v50
	v_mov_b32_e32 v31, v50
	v_mov_b32_e32 v32, v50
	v_mov_b32_e32 v33, v50
	v_mov_b32_e32 v18, v50
	v_mov_b32_e32 v19, v50
	v_mov_b32_e32 v20, v50
	v_mov_b32_e32 v21, v50
	v_mov_b32_e32 v22, v50
	v_mov_b32_e32 v23, v50
	v_mov_b32_e32 v24, v50
	v_mov_b32_e32 v25, v50
	v_mov_b32_e32 v10, v50
	v_mov_b32_e32 v11, v50
	v_mov_b32_e32 v12, v50
	v_mov_b32_e32 v13, v50
	v_mov_b32_e32 v14, v50
	v_mov_b32_e32 v15, v50
	v_mov_b32_e32 v16, v50
	v_mov_b32_e32 v17, v50
	v_mov_b32_e32 v2, v50
	v_mov_b32_e32 v3, v50
	v_mov_b32_e32 v4, v50
	v_mov_b32_e32 v5, v50
	v_mov_b32_e32 v6, v50
	v_mov_b32_e32 v7, v50
	v_mov_b32_e32 v8, v50
	v_mov_b32_e32 v9, v50
	v_mov_b32_e32 v106, v50
	v_mov_b32_e32 v107, v50
	v_mov_b32_e32 v108, v50
	v_mov_b32_e32 v109, v50
	v_mov_b32_e32 v118, v50
	v_mov_b32_e32 v119, v50
	v_mov_b32_e32 v120, v50
	v_mov_b32_e32 v121, v50
	v_mov_b32_e32 v98, v50
	v_mov_b32_e32 v99, v50
	v_mov_b32_e32 v100, v50
	v_mov_b32_e32 v101, v50
	v_mov_b32_e32 v102, v50
	v_mov_b32_e32 v103, v50
	v_mov_b32_e32 v104, v50
	v_mov_b32_e32 v105, v50
	v_mov_b32_e32 v78, v50
	v_mov_b32_e32 v79, v50
	v_mov_b32_e32 v80, v50
	v_mov_b32_e32 v81, v50
	v_mov_b32_e32 v94, v50
	v_mov_b32_e32 v95, v50
	v_mov_b32_e32 v96, v50
	v_mov_b32_e32 v97, v50
	v_mov_b32_e32 v74, v50
	v_mov_b32_e32 v75, v50
	v_mov_b32_e32 v76, v50
	v_mov_b32_e32 v77, v50
	v_mov_b32_e32 v90, v50
	v_mov_b32_e32 v91, v50
	v_mov_b32_e32 v92, v50
	v_mov_b32_e32 v93, v50
	v_mov_b32_e32 v134, v0
	v_mov_b32_e32 v132, v130
	v_and_b32_e32 v244, 63, v204
	v_lshrrev_b32_e32 v245, 6, v204
	v_and_b32_e32 v248, 15, v244
	v_lshrrev_b32_e32 v249, 4, v244
	v_and_b32_e32 v246, 7, v248
	v_lshrrev_b32_e32 v250, 3, v248
	v_lshlrev_b32_e32 v251, 7, v246
	v_lshl_add_u32 v251, v250, 10, v251
	v_xor_b32_e32 v247, v249, v246
	v_lshl_add_u32 v248, v247, 4, v251
	v_xor_b32_e32 v247, 4, v247
	v_lshl_add_u32 v250, v247, 4, v251
	v_lshrrev_b32_e32 v246, 2, v245
	v_lshl_add_u32 v141, v246, 13, v248
	v_lshl_add_u32 v241, v246, 13, v250
	v_and_b32_e32 v246, 3, v245
	v_lshl_add_u32 v140, v246, 12, v248
	v_lshl_add_u32 v240, v246, 12, v250
	s_barrier
	v_readlane_b32 s7, v236, 0

.LBB0_62:
	s_add_u32 s36, s42, s50
	s_addc_u32 s37, s43, s51
	s_add_u32 s36, s36, 0x100
	s_addc_u32 s37, s37, 0
	s_add_u32 s65, s23, s50
	s_addc_u32 s66, s24, s51
	s_add_i32 s67, 0, 0x10000
	s_cmpk_eq_i32 s50, 0xf00
	s_cselect_b32 s53, s47, s37
	s_cselect_b32 s52, s60, s36
	s_cselect_b32 s37, s45, s66
	s_cselect_b32 s36, s61, s65
	s_add_i32 s65, 0, 0x14000
	v_add_u32_e32 v154, s67, v140
	v_add_u32_e32 v242, s67, v240
	v_add_u32_e32 v158, s65, v140
	v_add_u32_e32 v243, s65, v240
	ds_read_b128 v[142:145], v154
	ds_read_b128 v[146:149], v242
	ds_read_b128 v[150:153], v154 offset:2048
	ds_read_b128 v[154:157], v242 offset:2048
	ds_read_b128 v[162:165], v158
	ds_read_b128 v[170:173], v243
	ds_read_b128 v[174:177], v158 offset:2048
	ds_read_b128 v[178:181], v243 offset:2048
	v_lshl_add_u64 v[158:159], v[138:139], 0, s[50:51]
	s_add_i32 m0, s82, 0xc000
	ds_read_b128 v[182:185], v141
	ds_read_b128 v[190:193], v241
	ds_read_b128 v[194:197], v141 offset:2048
	ds_read_b128 v[198:201], v241 offset:2048
	ds_read_b128 v[216:219], v141 offset:4096
	ds_read_b128 v[220:223], v241 offset:4096
	ds_read_b128 v[224:227], v141 offset:6144
	ds_read_b128 v[228:231], v241 offset:6144
	global_load_lds_dwordx4 v[158:159], off
	v_lshl_add_u64 v[158:159], v[136:137], 0, s[50:51]
	s_add_i32 m0, s82, 0xe000
	s_nop 0
	global_load_lds_dwordx4 v[158:159], off
	s_waitcnt vmcnt(8)
	s_waitcnt lgkmcnt(0)
	s_barrier
	s_setprio 1
	s_waitcnt lgkmcnt(0)
	v_mfma_f32_16x16x32_bf16 v[90:93], v[142:145], v[182:185], v[90:93]
	v_mfma_f32_16x16x32_bf16 v[74:77], v[150:153], v[182:185], v[74:77]
	v_mfma_f32_16x16x32_bf16 v[94:97], v[142:145], v[194:197], v[94:97]
	v_mfma_f32_16x16x32_bf16 v[78:81], v[150:153], v[194:197], v[78:81]
	v_mfma_f32_16x16x32_bf16 v[102:105], v[142:145], v[216:219], v[102:105]
	v_mfma_f32_16x16x32_bf16 v[98:101], v[150:153], v[216:219], v[98:101]
	v_mfma_f32_16x16x32_bf16 v[118:121], v[142:145], v[224:227], v[118:121]
	v_mfma_f32_16x16x32_bf16 v[106:109], v[150:153], v[224:227], v[106:109]
	v_mfma_f32_16x16x32_bf16 v[90:93], v[146:149], v[190:193], v[90:93]
	v_mfma_f32_16x16x32_bf16 v[74:77], v[154:157], v[190:193], v[74:77]
	v_mfma_f32_16x16x32_bf16 v[94:97], v[146:149], v[198:201], v[94:97]
	v_mfma_f32_16x16x32_bf16 v[78:81], v[154:157], v[198:201], v[78:81]
	v_mfma_f32_16x16x32_bf16 v[102:105], v[146:149], v[220:223], v[102:105]
	v_mfma_f32_16x16x32_bf16 v[98:101], v[154:157], v[220:223], v[98:101]
	v_mfma_f32_16x16x32_bf16 v[118:121], v[146:149], v[228:231], v[118:121]
	v_mfma_f32_16x16x32_bf16 v[106:109], v[154:157], v[228:231], v[106:109]
	s_setprio 0
	s_setprio 1
	v_mfma_f32_16x16x32_bf16 v[6:9], v[162:165], v[182:185], v[6:9]
	v_mfma_f32_16x16x32_bf16 v[2:5], v[174:177], v[182:185], v[2:5]
	v_mfma_f32_16x16x32_bf16 v[14:17], v[162:165], v[194:197], v[14:17]
	v_mfma_f32_16x16x32_bf16 v[10:13], v[174:177], v[194:197], v[10:13]
	v_mfma_f32_16x16x32_bf16 v[22:25], v[162:165], v[216:219], v[22:25]
	v_mfma_f32_16x16x32_bf16 v[18:21], v[174:177], v[216:219], v[18:21]
	v_mfma_f32_16x16x32_bf16 v[30:33], v[162:165], v[224:227], v[30:33]
	v_mfma_f32_16x16x32_bf16 v[26:29], v[174:177], v[224:227], v[26:29]
	v_mfma_f32_16x16x32_bf16 v[6:9], v[170:173], v[190:193], v[6:9]
	v_mfma_f32_16x16x32_bf16 v[2:5], v[178:181], v[190:193], v[2:5]
	v_mfma_f32_16x16x32_bf16 v[14:17], v[170:173], v[198:201], v[14:17]
	v_mfma_f32_16x16x32_bf16 v[10:13], v[178:181], v[198:201], v[10:13]
	v_mfma_f32_16x16x32_bf16 v[22:25], v[170:173], v[220:223], v[22:25]
	v_mfma_f32_16x16x32_bf16 v[18:21], v[178:181], v[220:223], v[18:21]
	v_mfma_f32_16x16x32_bf16 v[30:33], v[170:173], v[228:231], v[30:33]
	v_mfma_f32_16x16x32_bf16 v[26:29], v[178:181], v[228:231], v[26:29]
	s_setprio 0
	s_barrier
	s_add_i32 s66, s67, s80
	v_lshl_add_u64 v[158:159], s[36:37], 0, v[0:1]
	s_mov_b32 m0, s66
	ds_read_b128 v[182:185], v141 offset:16384
	ds_read_b128 v[190:193], v241 offset:16384
	ds_read_b128 v[194:197], v141 offset:18432
	ds_read_b128 v[198:201], v241 offset:18432
	ds_read_b128 v[216:219], v141 offset:20480
	ds_read_b128 v[220:223], v241 offset:20480
	ds_read_b128 v[224:227], v141 offset:22528
	ds_read_b128 v[228:231], v241 offset:22528
	global_load_lds_dwordx4 v[158:159], off
	s_add_i32 m0, s66, 0x2000
	s_add_u32 s66, s36, 0x80000
	v_lshl_add_u64 v[166:167], s[36:37], 0, v[130:131]
	s_addc_u32 s67, s37, 0
	s_add_i32 s65, s65, s80
	global_load_lds_dwordx4 v[166:167], off
	v_lshl_add_u64 v[202:203], s[66:67], 0, v[0:1]
	s_mov_b32 m0, s65
	v_lshl_add_u64 v[232:233], s[52:53], 0, v[130:131]
	global_load_lds_dwordx4 v[202:203], off
	v_lshl_add_u64 v[202:203], s[66:67], 0, v[130:131]
	s_add_i32 m0, s65, 0x2000
	s_nop 0
	global_load_lds_dwordx4 v[202:203], off
	v_lshl_add_u64 v[202:203], s[52:53], 0, v[0:1]
	s_mov_b32 m0, s82
	s_nop 0
	global_load_lds_dwordx4 v[202:203], off
	s_mov_b32 m0, s83
	s_nop 0
	global_load_lds_dwordx4 v[232:233], off
	s_waitcnt vmcnt(8)
	s_waitcnt lgkmcnt(0)
	s_barrier
	s_setprio 1
	s_waitcnt lgkmcnt(0)
	v_mfma_f32_16x16x32_bf16 v[126:129], v[142:145], v[182:185], v[126:129]
	v_mfma_f32_16x16x32_bf16 v[122:125], v[150:153], v[182:185], v[122:125]
	v_mfma_f32_16x16x32_bf16 v[114:117], v[142:145], v[194:197], v[114:117]
	v_mfma_f32_16x16x32_bf16 v[110:113], v[150:153], v[194:197], v[110:113]
	v_mfma_f32_16x16x32_bf16 v[86:89], v[142:145], v[216:219], v[86:89]
	v_mfma_f32_16x16x32_bf16 v[82:85], v[150:153], v[216:219], v[82:85]
	v_mfma_f32_16x16x32_bf16 v[70:73], v[142:145], v[224:227], v[70:73]
	v_mfma_f32_16x16x32_bf16 v[66:69], v[150:153], v[224:227], v[66:69]
	v_mfma_f32_16x16x32_bf16 v[126:129], v[146:149], v[190:193], v[126:129]
	v_mfma_f32_16x16x32_bf16 v[122:125], v[154:157], v[190:193], v[122:125]
	v_mfma_f32_16x16x32_bf16 v[114:117], v[146:149], v[198:201], v[114:117]
	v_mfma_f32_16x16x32_bf16 v[110:113], v[154:157], v[198:201], v[110:113]
	v_mfma_f32_16x16x32_bf16 v[86:89], v[146:149], v[220:223], v[86:89]
	v_mfma_f32_16x16x32_bf16 v[82:85], v[154:157], v[220:223], v[82:85]
	v_mfma_f32_16x16x32_bf16 v[70:73], v[146:149], v[228:231], v[70:73]
	v_mfma_f32_16x16x32_bf16 v[66:69], v[154:157], v[228:231], v[66:69]
	s_setprio 0
	s_setprio 1
	v_mfma_f32_16x16x32_bf16 v[38:41], v[162:165], v[182:185], v[38:41]
	v_mfma_f32_16x16x32_bf16 v[34:37], v[174:177], v[182:185], v[34:37]
	v_mfma_f32_16x16x32_bf16 v[46:49], v[162:165], v[194:197], v[46:49]
	v_mfma_f32_16x16x32_bf16 v[42:45], v[174:177], v[194:197], v[42:45]
	v_mfma_f32_16x16x32_bf16 v[62:65], v[162:165], v[216:219], v[62:65]
	v_mfma_f32_16x16x32_bf16 v[54:57], v[174:177], v[216:219], v[54:57]
	v_mfma_f32_16x16x32_bf16 v[58:61], v[162:165], v[224:227], v[58:61]
	v_mfma_f32_16x16x32_bf16 v[50:53], v[174:177], v[224:227], v[50:53]
	v_mfma_f32_16x16x32_bf16 v[38:41], v[170:173], v[190:193], v[38:41]
	v_mfma_f32_16x16x32_bf16 v[34:37], v[178:181], v[190:193], v[34:37]
	v_mfma_f32_16x16x32_bf16 v[46:49], v[170:173], v[198:201], v[46:49]
	v_mfma_f32_16x16x32_bf16 v[42:45], v[178:181], v[198:201], v[42:45]
	v_mfma_f32_16x16x32_bf16 v[62:65], v[170:173], v[220:223], v[62:65]
	v_mfma_f32_16x16x32_bf16 v[54:57], v[178:181], v[220:223], v[54:57]
	v_mfma_f32_16x16x32_bf16 v[58:61], v[170:173], v[228:231], v[58:61]
	v_mfma_f32_16x16x32_bf16 v[50:53], v[178:181], v[228:231], v[50:53]
	s_setprio 0
	s_barrier
	s_add_i32 s65, 0, 0x18000
	s_add_i32 s66, 0, 0x1c000
	v_add_u32_e32 v154, s65, v140
	v_add_u32_e32 v242, s65, v240
	v_add_u32_e32 v169, s66, v140
	v_add_u32_e32 v243, s66, v240
	ds_read_b128 v[142:145], v154
	ds_read_b128 v[146:149], v242
	ds_read_b128 v[150:153], v154 offset:2048
	ds_read_b128 v[154:157], v242 offset:2048
	ds_read_b128 v[162:165], v169
	ds_read_b128 v[170:173], v243
	ds_read_b128 v[174:177], v169 offset:2048
	ds_read_b128 v[178:181], v243 offset:2048
	s_add_u32 s52, s52, 0x80000
	s_addc_u32 s53, s53, 0
	s_mov_b32 m0, s84
	v_lshl_add_u64 v[234:235], s[52:53], 0, v[0:1]
	ds_read_b128 v[182:185], v141 offset:32768
	ds_read_b128 v[190:193], v241 offset:32768
	ds_read_b128 v[194:197], v141 offset:34816
	ds_read_b128 v[198:201], v241 offset:34816
	ds_read_b128 v[216:219], v141 offset:36864
	ds_read_b128 v[220:223], v241 offset:36864
	ds_read_b128 v[224:227], v141 offset:38912
	ds_read_b128 v[228:231], v241 offset:38912
	global_load_lds_dwordx4 v[234:235], off
	v_lshl_add_u64 v[234:235], s[52:53], 0, v[130:131]
	s_mov_b32 m0, s85
	s_nop 0
	global_load_lds_dwordx4 v[234:235], off
	s_waitcnt vmcnt(8)
	s_waitcnt lgkmcnt(0)
	s_barrier
	s_setprio 1
	s_waitcnt lgkmcnt(0)
	v_mfma_f32_16x16x32_bf16 v[90:93], v[142:145], v[182:185], v[90:93]
	v_mfma_f32_16x16x32_bf16 v[74:77], v[150:153], v[182:185], v[74:77]
	v_mfma_f32_16x16x32_bf16 v[94:97], v[142:145], v[194:197], v[94:97]
	v_mfma_f32_16x16x32_bf16 v[78:81], v[150:153], v[194:197], v[78:81]
	v_mfma_f32_16x16x32_bf16 v[102:105], v[142:145], v[216:219], v[102:105]
	v_mfma_f32_16x16x32_bf16 v[98:101], v[150:153], v[216:219], v[98:101]
	v_mfma_f32_16x16x32_bf16 v[118:121], v[142:145], v[224:227], v[118:121]
	v_mfma_f32_16x16x32_bf16 v[106:109], v[150:153], v[224:227], v[106:109]
	v_mfma_f32_16x16x32_bf16 v[90:93], v[146:149], v[190:193], v[90:93]
	v_mfma_f32_16x16x32_bf16 v[74:77], v[154:157], v[190:193], v[74:77]
	v_mfma_f32_16x16x32_bf16 v[94:97], v[146:149], v[198:201], v[94:97]
	v_mfma_f32_16x16x32_bf16 v[78:81], v[154:157], v[198:201], v[78:81]
	v_mfma_f32_16x16x32_bf16 v[102:105], v[146:149], v[220:223], v[102:105]
	v_mfma_f32_16x16x32_bf16 v[98:101], v[154:157], v[220:223], v[98:101]
	v_mfma_f32_16x16x32_bf16 v[118:121], v[146:149], v[228:231], v[118:121]
	v_mfma_f32_16x16x32_bf16 v[106:109], v[154:157], v[228:231], v[106:109]
	s_setprio 0
	s_setprio 1
	v_mfma_f32_16x16x32_bf16 v[6:9], v[162:165], v[182:185], v[6:9]
	v_mfma_f32_16x16x32_bf16 v[2:5], v[174:177], v[182:185], v[2:5]
	v_mfma_f32_16x16x32_bf16 v[14:17], v[162:165], v[194:197], v[14:17]
	v_mfma_f32_16x16x32_bf16 v[10:13], v[174:177], v[194:197], v[10:13]
	v_mfma_f32_16x16x32_bf16 v[22:25], v[162:165], v[216:219], v[22:25]
	v_mfma_f32_16x16x32_bf16 v[18:21], v[174:177], v[216:219], v[18:21]
	v_mfma_f32_16x16x32_bf16 v[30:33], v[162:165], v[224:227], v[30:33]
	v_mfma_f32_16x16x32_bf16 v[26:29], v[174:177], v[224:227], v[26:29]
	v_mfma_f32_16x16x32_bf16 v[6:9], v[170:173], v[190:193], v[6:9]
	v_mfma_f32_16x16x32_bf16 v[2:5], v[178:181], v[190:193], v[2:5]
	v_mfma_f32_16x16x32_bf16 v[14:17], v[170:173], v[198:201], v[14:17]
	v_mfma_f32_16x16x32_bf16 v[10:13], v[178:181], v[198:201], v[10:13]
	v_mfma_f32_16x16x32_bf16 v[22:25], v[170:173], v[220:223], v[22:25]
	v_mfma_f32_16x16x32_bf16 v[18:21], v[178:181], v[220:223], v[18:21]
	v_mfma_f32_16x16x32_bf16 v[30:33], v[170:173], v[228:231], v[30:33]
	v_mfma_f32_16x16x32_bf16 v[26:29], v[178:181], v[228:231], v[26:29]
	s_setprio 0
	s_barrier
	s_add_i32 s52, s65, s80
	v_lshl_add_u64 v[158:159], v[158:159], 0, s[20:21]
	s_mov_b32 m0, s52
	ds_read_b128 v[182:185], v141 offset:49152
	ds_read_b128 v[190:193], v241 offset:49152
	ds_read_b128 v[194:197], v141 offset:51200
	ds_read_b128 v[198:201], v241 offset:51200
	ds_read_b128 v[216:219], v141 offset:53248
	ds_read_b128 v[220:223], v241 offset:53248
	ds_read_b128 v[224:227], v141 offset:55296
	ds_read_b128 v[228:231], v241 offset:55296
	global_load_lds_dwordx4 v[158:159], off
	s_add_i32 m0, s52, 0x2000
	s_add_u32 s36, s36, 0x80080
	v_lshl_add_u64 v[158:159], v[166:167], 0, s[20:21]
	s_addc_u32 s37, s37, 0
	s_add_i32 s52, s66, s80
	global_load_lds_dwordx4 v[158:159], off
	v_lshl_add_u64 v[158:159], s[36:37], 0, v[0:1]
	s_mov_b32 m0, s52
	s_nop 0
	global_load_lds_dwordx4 v[158:159], off
	v_lshl_add_u64 v[158:159], s[36:37], 0, v[130:131]
	s_add_i32 m0, s52, 0x2000
	s_nop 0
	global_load_lds_dwordx4 v[158:159], off
	v_lshl_add_u64 v[158:159], v[202:203], 0, s[20:21]
	s_mov_b32 m0, s14
	s_nop 0
	global_load_lds_dwordx4 v[158:159], off
	v_lshl_add_u64 v[158:159], v[232:233], 0, s[20:21]
	s_mov_b32 m0, s15
	s_nop 0
	global_load_lds_dwordx4 v[158:159], off
	s_waitcnt vmcnt(8)
	s_waitcnt lgkmcnt(0)
	s_barrier
	s_setprio 1
	s_waitcnt lgkmcnt(0)
	v_mfma_f32_16x16x32_bf16 v[126:129], v[142:145], v[182:185], v[126:129]
	v_mfma_f32_16x16x32_bf16 v[122:125], v[150:153], v[182:185], v[122:125]
	v_mfma_f32_16x16x32_bf16 v[114:117], v[142:145], v[194:197], v[114:117]
	v_mfma_f32_16x16x32_bf16 v[110:113], v[150:153], v[194:197], v[110:113]
	v_mfma_f32_16x16x32_bf16 v[86:89], v[142:145], v[216:219], v[86:89]
	v_mfma_f32_16x16x32_bf16 v[82:85], v[150:153], v[216:219], v[82:85]
	v_mfma_f32_16x16x32_bf16 v[70:73], v[142:145], v[224:227], v[70:73]
	v_mfma_f32_16x16x32_bf16 v[66:69], v[150:153], v[224:227], v[66:69]
	v_mfma_f32_16x16x32_bf16 v[126:129], v[146:149], v[190:193], v[126:129]
	v_mfma_f32_16x16x32_bf16 v[122:125], v[154:157], v[190:193], v[122:125]
	v_mfma_f32_16x16x32_bf16 v[114:117], v[146:149], v[198:201], v[114:117]
	v_mfma_f32_16x16x32_bf16 v[110:113], v[154:157], v[198:201], v[110:113]
	v_mfma_f32_16x16x32_bf16 v[86:89], v[146:149], v[220:223], v[86:89]
	v_mfma_f32_16x16x32_bf16 v[82:85], v[154:157], v[220:223], v[82:85]
	v_mfma_f32_16x16x32_bf16 v[70:73], v[146:149], v[228:231], v[70:73]
	v_mfma_f32_16x16x32_bf16 v[66:69], v[154:157], v[228:231], v[66:69]
	s_setprio 0
	s_setprio 1
	v_mfma_f32_16x16x32_bf16 v[38:41], v[162:165], v[182:185], v[38:41]
	v_mfma_f32_16x16x32_bf16 v[34:37], v[174:177], v[182:185], v[34:37]
	v_mfma_f32_16x16x32_bf16 v[46:49], v[162:165], v[194:197], v[46:49]
	v_mfma_f32_16x16x32_bf16 v[42:45], v[174:177], v[194:197], v[42:45]
	v_mfma_f32_16x16x32_bf16 v[62:65], v[162:165], v[216:219], v[62:65]
	v_mfma_f32_16x16x32_bf16 v[54:57], v[174:177], v[216:219], v[54:57]
	v_mfma_f32_16x16x32_bf16 v[58:61], v[162:165], v[224:227], v[58:61]
	v_mfma_f32_16x16x32_bf16 v[50:53], v[174:177], v[224:227], v[50:53]
	v_mfma_f32_16x16x32_bf16 v[38:41], v[170:173], v[190:193], v[38:41]
	v_mfma_f32_16x16x32_bf16 v[34:37], v[178:181], v[190:193], v[34:37]
	v_mfma_f32_16x16x32_bf16 v[46:49], v[170:173], v[198:201], v[46:49]
	v_mfma_f32_16x16x32_bf16 v[42:45], v[178:181], v[198:201], v[42:45]
	v_mfma_f32_16x16x32_bf16 v[62:65], v[170:173], v[220:223], v[62:65]
	v_mfma_f32_16x16x32_bf16 v[54:57], v[178:181], v[220:223], v[54:57]
	v_mfma_f32_16x16x32_bf16 v[58:61], v[170:173], v[228:231], v[58:61]
	v_mfma_f32_16x16x32_bf16 v[50:53], v[178:181], v[228:231], v[50:53]
	s_setprio 0
	s_barrier
	s_add_i32 s64, s64, 2
	s_add_u32 s50, s50, 0x100
	s_addc_u32 s51, s51, 0
	s_cmp_gt_u32 s64, 29
	s_cbranch_scc0 .LBB0_62
	s_add_u32 s36, s23, 0xffffff00
	s_addc_u32 s37, s24, -1
	s_andn2_b64 vcc, exec, s[40:41]
	s_cbranch_vccnz .LBB0_65
	v_mov_b32_e32 v50, 0
	s_mov_b32 s0, s44
	s_mov_b32 s55, s46
	s_mov_b64 s[42:43], s[48:49]
	s_mov_b32 s25, s22
	v_mov_b32_e32 v51, v50
	v_mov_b32_e32 v52, v50
	v_mov_b32_e32 v53, v50
	v_mov_b32_e32 v58, v50
	v_mov_b32_e32 v59, v50
	v_mov_b32_e32 v60, v50
	v_mov_b32_e32 v61, v50
	v_mov_b32_e32 v54, v50
	v_mov_b32_e32 v55, v50
	v_mov_b32_e32 v56, v50
	v_mov_b32_e32 v57, v50
	v_mov_b32_e32 v62, v50
	v_mov_b32_e32 v63, v50
	v_mov_b32_e32 v64, v50
	v_mov_b32_e32 v65, v50
	v_mov_b32_e32 v42, v50
	v_mov_b32_e32 v43, v50
	v_mov_b32_e32 v44, v50
	v_mov_b32_e32 v45, v50
	v_mov_b32_e32 v46, v50
	v_mov_b32_e32 v47, v50
	v_mov_b32_e32 v48, v50
	v_mov_b32_e32 v49, v50
	v_mov_b32_e32 v34, v50
	v_mov_b32_e32 v35, v50
	v_mov_b32_e32 v36, v50
	v_mov_b32_e32 v37, v50
	v_mov_b32_e32 v38, v50
	v_mov_b32_e32 v39, v50
	v_mov_b32_e32 v40, v50
	v_mov_b32_e32 v41, v50
	v_mov_b32_e32 v66, v50
	v_mov_b32_e32 v67, v50
	v_mov_b32_e32 v68, v50
	v_mov_b32_e32 v69, v50
	v_mov_b32_e32 v70, v50
	v_mov_b32_e32 v71, v50
	v_mov_b32_e32 v72, v50
	v_mov_b32_e32 v73, v50
	v_mov_b32_e32 v82, v50
	v_mov_b32_e32 v83, v50
	v_mov_b32_e32 v84, v50
	v_mov_b32_e32 v85, v50
	v_mov_b32_e32 v86, v50
	v_mov_b32_e32 v87, v50
	v_mov_b32_e32 v88, v50
	v_mov_b32_e32 v89, v50
	v_mov_b32_e32 v110, v50
	v_mov_b32_e32 v111, v50
	v_mov_b32_e32 v112, v50
	v_mov_b32_e32 v113, v50
	v_mov_b32_e32 v114, v50
	v_mov_b32_e32 v115, v50
	v_mov_b32_e32 v116, v50
	v_mov_b32_e32 v117, v50
	v_mov_b32_e32 v122, v50
	v_mov_b32_e32 v123, v50
	v_mov_b32_e32 v124, v50
	v_mov_b32_e32 v125, v50
	v_mov_b32_e32 v126, v50
	v_mov_b32_e32 v127, v50
	v_mov_b32_e32 v128, v50
	v_mov_b32_e32 v129, v50
	v_mov_b32_e32 v26, v50
	v_mov_b32_e32 v27, v50
	v_mov_b32_e32 v28, v50
	v_mov_b32_e32 v29, v50
	v_mov_b32_e32 v30, v50
	v_mov_b32_e32 v31, v50
	v_mov_b32_e32 v32, v50
	v_mov_b32_e32 v33, v50
	v_mov_b32_e32 v18, v50
	v_mov_b32_e32 v19, v50
	v_mov_b32_e32 v20, v50
	v_mov_b32_e32 v21, v50
	v_mov_b32_e32 v22, v50
	v_mov_b32_e32 v23, v50
	v_mov_b32_e32 v24, v50
	v_mov_b32_e32 v25, v50
	v_mov_b32_e32 v10, v50
	v_mov_b32_e32 v11, v50
	v_mov_b32_e32 v12, v50
	v_mov_b32_e32 v13, v50
	v_mov_b32_e32 v14, v50
	v_mov_b32_e32 v15, v50
	v_mov_b32_e32 v16, v50
	v_mov_b32_e32 v17, v50
	v_mov_b32_e32 v2, v50
	v_mov_b32_e32 v3, v50
	v_mov_b32_e32 v4, v50
	v_mov_b32_e32 v5, v50
	v_mov_b32_e32 v6, v50
	v_mov_b32_e32 v7, v50
	v_mov_b32_e32 v8, v50
	v_mov_b32_e32 v9, v50
	v_mov_b32_e32 v106, v50
	v_mov_b32_e32 v107, v50
	v_mov_b32_e32 v108, v50
	v_mov_b32_e32 v109, v50
	v_mov_b32_e32 v118, v50
	v_mov_b32_e32 v119, v50
	v_mov_b32_e32 v120, v50
	v_mov_b32_e32 v121, v50
	v_mov_b32_e32 v98, v50
	v_mov_b32_e32 v99, v50
	v_mov_b32_e32 v100, v50
	v_mov_b32_e32 v101, v50
	v_mov_b32_e32 v102, v50
	v_mov_b32_e32 v103, v50
	v_mov_b32_e32 v104, v50
	v_mov_b32_e32 v105, v50
	v_mov_b32_e32 v78, v50
	v_mov_b32_e32 v79, v50
	v_mov_b32_e32 v80, v50
	v_mov_b32_e32 v81, v50
	v_mov_b32_e32 v94, v50
	v_mov_b32_e32 v95, v50
	v_mov_b32_e32 v96, v50
	v_mov_b32_e32 v97, v50
	v_mov_b32_e32 v74, v50
	v_mov_b32_e32 v75, v50
	v_mov_b32_e32 v76, v50
	v_mov_b32_e32 v77, v50
	v_mov_b32_e32 v90, v50
	v_mov_b32_e32 v91, v50
	v_mov_b32_e32 v92, v50
	v_mov_b32_e32 v93, v50
	s_branch .LBB0_66

.LBB0_457:
	v_ashrrev_i32_e32 v0, 31, v10
	v_lshrrev_b32_e32 v0, 26, v0
	v_add_u32_e32 v0, v10, v0
	v_ashrrev_i32_e32 v11, 6, v0
	v_bfe_i32 v0, v10, 27, 1
	v_lshlrev_b32_e32 v2, 4, v10
	v_lshrrev_b32_e32 v0, 22, v0
	v_add_u32_e32 v0, v2, v0
	v_and_b32_e32 v0, 0xfffffc00, v0
	v_sub_u32_e32 v0, v2, v0
	v_lshrrev_b32_e32 v3, 4, v0
	v_bitop3_b32 v0, v3, v0, 32 bitop3:0x6c
	v_ashrrev_i32_e32 v4, 31, v0
	v_lshrrev_b32_e32 v4, 26, v4
	v_add_u32_e32 v4, v0, v4
	v_lshlrev_b32_e32 v3, 3, v11
	v_ashrrev_i32_e32 v12, 6, v4
	v_and_b32_e32 v4, 0xc0, v4
	v_and_b32_e32 v3, -16, v3
	v_sub_u32_e32 v0, v0, v4
	v_add_u32_e32 v3, v12, v3
	v_ashrrev_i16_sdwa v0, v205, sext(v0) dst_sel:DWORD dst_unused:UNUSED_PAD src0_sel:DWORD src1_sel:BYTE_0
	v_lshlrev_b32_e32 v5, 5, v11
	v_bfe_i32 v13, v0, 0, 16
	v_lshlrev_b32_e32 v0, 1, v3
	v_lshrrev_b32_e32 v4, 2, v3
	v_and_b32_e32 v6, 3, v12
	s_mov_b32 s23, 0xfffe0
	v_and_b32_e32 v5, 32, v5
	v_and_b32_e32 v0, 24, v0
	v_and_b32_e32 v4, 4, v4
	v_and_or_b32 v6, v3, s23, v6
	v_or3_b32 v0, v6, v4, v0
	v_add_lshl_u32 v4, v5, v13, 1
	v_add_u32_e32 v2, 0x2000, v2
	v_lshl_add_u32 v130, v3, 12, v4
	v_ashrrev_i32_e32 v3, 31, v2
	v_lshrrev_b32_e32 v3, 22, v3
	v_add_u32_e32 v3, v2, v3
	v_ashrrev_i32_e32 v14, 10, v3
	v_mul_i32_i24_e32 v3, 0x400, v14
	v_sub_u32_e32 v2, v2, v3
	v_lshrrev_b32_e32 v3, 4, v2
	v_bitop3_b32 v2, v3, v2, 32 bitop3:0x6c
	v_lshl_add_u32 v0, v0, 12, v4
	v_ashrrev_i32_e32 v4, 31, v2
	v_lshrrev_b32_e32 v4, 26, v4
	v_add_u32_e32 v4, v2, v4
	v_lshlrev_b32_e32 v3, 3, v14
	v_ashrrev_i32_e32 v15, 6, v4
	v_and_b32_e32 v4, 0xc0, v4
	v_and_b32_e32 v3, -16, v3
	v_sub_u32_e32 v2, v2, v4
	v_add_u32_e32 v3, v15, v3
	v_ashrrev_i16_sdwa v2, v205, sext(v2) dst_sel:DWORD dst_unused:UNUSED_PAD src0_sel:DWORD src1_sel:BYTE_0
	v_bfe_i32 v16, v2, 0, 16
	v_lshlrev_b32_e32 v2, 1, v3
	v_lshrrev_b32_e32 v4, 2, v3
	v_and_b32_e32 v6, 3, v15
	v_and_b32_e32 v2, 24, v2
	v_and_b32_e32 v4, 4, v4
	v_and_or_b32 v6, v3, s23, v6
	s_lshl_b32 s22, s22, 3
	v_or3_b32 v2, v6, v4, v2
	v_cvt_f32_u32_e32 v4, s22
	v_lshlrev_b32_e32 v5, 5, v14
	v_and_b32_e32 v5, 32, v5
	v_add_lshl_u32 v5, v5, v16, 1
	v_lshl_add_u32 v134, v2, 12, v5
	v_rcp_iflag_f32_e32 v2, v4
	s_add_i32 s18, s24, s18
	s_sub_i32 s24, 0, s22
	s_abs_i32 s39, s18
	v_mul_f32_e32 v2, 0x4f7ffffe, v2
	v_cvt_u32_f32_e32 v2, v2
	s_ashr_i32 s37, s36, 6
	s_ashr_i32 s19, s36, 8
	s_lshl_b32 s23, s37, 10
	v_readfirstlane_b32 s60, v2
	s_mul_i32 s24, s24, s60
	s_mul_hi_u32 s24, s60, s24
	s_add_i32 s24, s60, s24
	s_mul_hi_u32 s60, s39, s24
	s_mul_i32 s61, s60, s22
	s_sub_i32 s39, s39, s61
	s_ashr_i32 s38, s18, 31
	s_add_i32 s61, s60, 1
	s_sub_i32 s64, s39, s22
	s_cmp_ge_u32 s39, s22
	s_cselect_b32 s60, s61, s60
	s_cselect_b32 s39, s64, s39
	s_add_i32 s61, s60, 1
	s_cmp_ge_u32 s39, s22
	s_cselect_b32 s39, s61, s60
	s_xor_b32 s39, s39, s38
	s_sub_i32 s38, s39, s38
	s_lshl_b32 s60, s38, 3
	s_sub_i32 s39, s89, s60
	s_min_i32 s61, s39, 8
	s_sext_i32_i16 s39, s61
	v_cvt_f32_i32_e32 v2, s39
	s_mul_i32 s38, s38, s22
	s_sub_i32 s64, s18, s38
	s_sext_i32_i16 s18, s64
	v_lshl_add_u32 v132, v3, 12, v5
	v_cvt_f32_i32_e32 v3, s18
	v_rcp_iflag_f32_e32 v4, v2
	s_xor_b32 s18, s18, s39
	s_ashr_i32 s18, s18, 30
	s_or_b32 s18, s18, 1
	v_mul_f32_e32 v4, v3, v4
	v_trunc_f32_e32 v4, v4
	v_fma_f32 v3, -v4, v2, v3
	v_cvt_i32_f32_e32 v4, v4
	v_cmp_ge_f32_e64 s[38:39], |v3|, |v2|
	s_and_b64 s[38:39], s[38:39], exec
	s_cselect_b32 s18, s18, 0
	v_readfirstlane_b32 s38, v4
	s_add_i32 s18, s38, s18
	s_mul_i32 s38, s18, s61
	s_sub_i32 s38, s64, s38
	s_sext_i32_i16 s38, s38
	s_add_i32 s80, s60, s38
	s_ashr_i32 s81, s80, 31
	s_bfe_i64 s[60:61], s[18:19], 0x100000
	s_lshl_b64 s[38:39], s[80:81], 20
	s_lshl_b64 s[60:61], s[60:61], 20
	s_add_u32 s82, s52, s60
	s_addc_u32 s83, s53, s61
	s_add_i32 s81, s23, 0
	s_add_i32 m0, s81, 0x10000
	v_mov_b32_e32 v135, v1
	v_and_b32_e32 v244, 63, v204
	v_lshrrev_b32_e32 v245, 6, v204
	v_lshrrev_b32_e32 v246, 3, v244
	v_and_b32_e32 v247, 7, v244
	v_xor_b32_e32 v247, v247, v246
	v_lshlrev_b32_e32 v247, 4, v247
	v_lshl_add_u32 v248, v245, 3, v246
	v_lshl_add_u32 v130, v248, 12, v247
	v_add_u32_e32 v132, 0x40000, v130
	v_and_b32_e32 v249, 1, v245
	v_lshlrev_b32_e32 v249, 1, v249
	v_lshrrev_b32_e32 v250, 5, v244
	v_add_u32_e32 v249, v249, v250
	v_lshlrev_b32_e32 v249, 3, v249
	v_bfe_u32 v250, v245, 1, 1
	v_lshl_add_u32 v249, v250, 2, v249
	v_and_b32_e32 v250, 3, v246
	v_add_u32_e32 v249, v249, v250
	v_lshrrev_b32_e32 v250, 2, v245
	v_lshl_add_u32 v249, v250, 5, v249
	v_lshl_add_u32 v0, v249, 12, v247
	v_add_u32_e32 v134, 0x40000, v0
	global_load_lds_dwordx4 v0, s[82:83]
	s_add_i32 m0, s81, 0x12000
	s_add_u32 s60, s82, 0x80000
	global_load_lds_dwordx4 v134, s[82:83]
	s_addc_u32 s61, s83, 0
	s_add_i32 m0, s81, 0x14000
	v_mov_b32_e32 v131, v1
	global_load_lds_dwordx4 v0, s[60:61]
	s_add_i32 m0, s81, 0x16000
	s_add_u32 s76, s54, s38
	global_load_lds_dwordx4 v134, s[60:61]
	s_addc_u32 s77, s55, s39
	s_add_i32 s60, s81, 0x2000
	s_mov_b32 m0, s81
	s_add_u32 s38, s76, 0x80000
	global_load_lds_dwordx4 v130, s[76:77]
	s_mov_b32 m0, s60
	s_addc_u32 s39, s77, 0
	s_add_i32 s61, s81, 0x4000
	global_load_lds_dwordx4 v132, s[76:77]
	s_mov_b32 m0, s61
	s_add_i32 s64, s81, 0x6000
	global_load_lds_dwordx4 v130, s[38:39]
	s_mov_b32 m0, s64
	v_mov_b32_e32 v133, v1
	global_load_lds_dwordx4 v132, s[38:39]
	s_cmp_eq_u32 s19, 1
	s_mov_b64 s[6:7], s[92:93]
	v_lshl_add_u64 v[8:9], s[82:83], 0, v[0:1]
	v_lshl_add_u64 v[6:7], s[82:83], 0, v[134:135]
	v_lshl_add_u64 v[2:3], s[76:77], 0, v[130:131]
	s_cselect_b64 s[90:91], -1, 0
	s_cmp_lg_u32 s19, 1
	v_lshl_add_u64 v[4:5], s[76:77], 0, v[132:133]
	s_cbranch_scc1 .LBB0_459
	s_barrier
.LBB0_459:
	s_lshl_b32 s37, s37, 5
	s_and_b32 s37, s37, 0x60
	s_add_i32 m0, s81, 0x18000
	v_lshl_add_u64 v[8:9], v[8:9], 0, s[20:21]
	s_lshl_b32 s67, s19, 13
	s_lshl_b32 s69, s37, 7
	s_waitcnt vmcnt(2)
	s_barrier
	global_load_lds_dwordx4 v[8:9], off
	v_lshl_add_u64 v[6:7], v[6:7], 0, s[20:21]
	s_add_i32 m0, s81, 0x1a000
	s_add_i32 s65, s81, 0x8000
	s_add_i32 s66, s81, 0xa000
	global_load_lds_dwordx4 v[6:7], off
	v_lshl_add_u64 v[2:3], v[2:3], 0, s[20:21]
	s_mov_b32 m0, s65
	s_add_u32 s38, s82, 0x80080
	global_load_lds_dwordx4 v[2:3], off
	v_lshl_add_u64 v[2:3], v[4:5], 0, s[20:21]
	s_mov_b32 m0, s66
	s_addc_u32 s39, s83, 0
	global_load_lds_dwordx4 v[2:3], off
	s_add_i32 m0, s81, 0x1c000
	v_lshl_add_u64 v[2:3], s[38:39], 0, v[0:1]
	global_load_lds_dwordx4 v[2:3], off
	v_lshl_add_u64 v[2:3], s[38:39], 0, v[134:135]
	s_add_i32 m0, s81, 0x1e000
	s_cmpk_lt_u32 s36, 0x100
	global_load_lds_dwordx4 v[2:3], off
	v_lshrrev_b32_e32 v3, 1, v10
	v_and_b32_e32 v3, 24, v3
	v_and_b32_e32 v2, 15, v10
	v_lshlrev_b32_e32 v4, 1, v3
	v_lshl_or_b32 v142, s19, 6, v2
	v_lshl_or_b32 v2, v2, 6, v4
	v_lshlrev_b32_e32 v4, 2, v10
	v_and_b32_e32 v4, 32, v4
	v_bitop3_b32 v5, v2, s67, v4 bitop3:0xde
	v_bitop3_b32 v143, v2, s69, v4 bitop3:0xde
	v_lshlrev_b32_e32 v2, 15, v14
	v_and_b32_e32 v2, 0xffff0000, v2
	v_or_b32_e32 v144, s37, v3
	v_lshl_add_u32 v2, v15, 12, v2
	v_and_b32_e32 v3, 1, v14
	v_lshl_or_b32 v2, v3, 6, v2
	v_lshl_add_u32 v136, v16, 1, v2
	v_lshlrev_b32_e32 v2, 15, v11
	v_and_b32_e32 v2, 0xffff0000, v2
	s_waitcnt vmcnt(6)
	v_lshl_add_u32 v2, v12, 12, v2
	v_and_b32_e32 v3, 1, v11
	v_lshl_or_b32 v2, v3, 6, v2
	s_sext_i32_i16 s68, s18
	s_cselect_b64 s[94:95], -1, 0
	v_mov_b32_e32 v137, v1
	v_lshl_add_u32 v138, v13, 1, v2
	v_mov_b32_e32 v139, v1
	s_mov_b32 s67, 0
	v_add_u32_e32 v145, 0, v5
	v_mov_b32_e32 v138, v130
	v_mov_b32_e32 v136, v132
	v_and_b32_e32 v244, 63, v204
	v_lshrrev_b32_e32 v245, 6, v204
	v_and_b32_e32 v248, 15, v244
	v_lshrrev_b32_e32 v249, 4, v244
	v_and_b32_e32 v246, 7, v248
	v_lshrrev_b32_e32 v250, 3, v248
	v_lshlrev_b32_e32 v251, 7, v246
	v_lshl_add_u32 v251, v250, 10, v251
	v_xor_b32_e32 v247, v249, v246
	v_lshl_add_u32 v248, v247, 4, v251
	v_xor_b32_e32 v247, 4, v247
	v_lshl_add_u32 v250, v247, 4, v251
	v_lshrrev_b32_e32 v246, 2, v245
	v_lshl_add_u32 v145, v246, 13, v248
	v_lshl_add_u32 v241, v246, 13, v250
	v_and_b32_e32 v246, 3, v245
	v_lshl_add_u32 v143, v246, 12, v248
	v_lshl_add_u32 v240, v246, 12, v250
	s_barrier
	s_branch .LBB0_462

.LBB0_469:
	s_add_u32 s76, s82, 0xfff80080
	s_addc_u32 s77, s83, -1
	s_add_i32 s93, 0, 0x10000
	s_cmp_eq_u32 s74, 28
	s_cselect_b32 vcc_hi, s19, s77
	s_cselect_b32 vcc_lo, s69, s76
	v_add_u32_e32 v140, s93, v143
	v_add_u32_e32 v242, s93, v240
	s_cselect_b32 s77, s70, s73
	s_cselect_b32 s76, s71, s72
	s_add_i32 s75, 0, 0x14000
	ds_read_b128 v[146:149], v140
	ds_read_b128 v[150:153], v242
	ds_read_b128 v[154:157], v140 offset:2048
	ds_read_b128 v[158:161], v242 offset:2048
	v_add_u32_e32 v140, s75, v143
	v_add_u32_e32 v243, s75, v240
	ds_read_b128 v[162:165], v140
	ds_read_b128 v[166:169], v243
	ds_read_b128 v[170:173], v140 offset:2048
	ds_read_b128 v[174:177], v243 offset:2048
	v_lshl_add_u64 v[140:141], s[82:83], 0, v[138:139]
	s_add_i32 m0, s81, 0xc000
	ds_read_b128 v[178:181], v145
	ds_read_b128 v[182:185], v241
	ds_read_b128 v[190:193], v145 offset:2048
	ds_read_b128 v[194:197], v241 offset:2048
	ds_read_b128 v[198:201], v145 offset:4096
	ds_read_b128 v[216:219], v241 offset:4096
	ds_read_b128 v[220:223], v145 offset:6144
	ds_read_b128 v[224:227], v241 offset:6144
	global_load_lds_dwordx4 v[140:141], off
	v_lshl_add_u64 v[140:141], s[82:83], 0, v[136:137]
	s_add_i32 m0, s81, 0xe000
	s_nop 0
	global_load_lds_dwordx4 v[140:141], off
	s_waitcnt vmcnt(8)
	s_waitcnt lgkmcnt(0)
	s_barrier
	s_setprio 1
	s_waitcnt lgkmcnt(0)
	v_mfma_f32_16x16x32_bf16 v[126:129], v[146:149], v[178:181], v[126:129]
	v_mfma_f32_16x16x32_bf16 v[122:125], v[154:157], v[178:181], v[122:125]
	v_mfma_f32_16x16x32_bf16 v[114:117], v[146:149], v[190:193], v[114:117]
	v_mfma_f32_16x16x32_bf16 v[106:109], v[154:157], v[190:193], v[106:109]
	v_mfma_f32_16x16x32_bf16 v[98:101], v[146:149], v[198:201], v[98:101]
	v_mfma_f32_16x16x32_bf16 v[90:93], v[154:157], v[198:201], v[90:93]
	v_mfma_f32_16x16x32_bf16 v[82:85], v[146:149], v[220:223], v[82:85]
	v_mfma_f32_16x16x32_bf16 v[74:77], v[154:157], v[220:223], v[74:77]
	v_mfma_f32_16x16x32_bf16 v[126:129], v[150:153], v[182:185], v[126:129]
	v_mfma_f32_16x16x32_bf16 v[122:125], v[158:161], v[182:185], v[122:125]
	v_mfma_f32_16x16x32_bf16 v[114:117], v[150:153], v[194:197], v[114:117]
	v_mfma_f32_16x16x32_bf16 v[106:109], v[158:161], v[194:197], v[106:109]
	v_mfma_f32_16x16x32_bf16 v[98:101], v[150:153], v[216:219], v[98:101]
	v_mfma_f32_16x16x32_bf16 v[90:93], v[158:161], v[216:219], v[90:93]
	v_mfma_f32_16x16x32_bf16 v[82:85], v[150:153], v[224:227], v[82:85]
	v_mfma_f32_16x16x32_bf16 v[74:77], v[158:161], v[224:227], v[74:77]
	s_setprio 0
	s_setprio 1
	v_mfma_f32_16x16x32_bf16 v[118:121], v[162:165], v[178:181], v[118:121]
	v_mfma_f32_16x16x32_bf16 v[110:113], v[170:173], v[178:181], v[110:113]
	v_mfma_f32_16x16x32_bf16 v[102:105], v[162:165], v[190:193], v[102:105]
	v_mfma_f32_16x16x32_bf16 v[94:97], v[170:173], v[190:193], v[94:97]
	v_mfma_f32_16x16x32_bf16 v[86:89], v[162:165], v[198:201], v[86:89]
	v_mfma_f32_16x16x32_bf16 v[78:81], v[170:173], v[198:201], v[78:81]
	v_mfma_f32_16x16x32_bf16 v[70:73], v[162:165], v[220:223], v[70:73]
	v_mfma_f32_16x16x32_bf16 v[66:69], v[170:173], v[220:223], v[66:69]
	v_mfma_f32_16x16x32_bf16 v[118:121], v[166:169], v[182:185], v[118:121]
	v_mfma_f32_16x16x32_bf16 v[110:113], v[174:177], v[182:185], v[110:113]
	v_mfma_f32_16x16x32_bf16 v[102:105], v[166:169], v[194:197], v[102:105]
	v_mfma_f32_16x16x32_bf16 v[94:97], v[174:177], v[194:197], v[94:97]
	v_mfma_f32_16x16x32_bf16 v[86:89], v[166:169], v[216:219], v[86:89]
	v_mfma_f32_16x16x32_bf16 v[78:81], v[174:177], v[216:219], v[78:81]
	v_mfma_f32_16x16x32_bf16 v[70:73], v[166:169], v[224:227], v[70:73]
	v_mfma_f32_16x16x32_bf16 v[66:69], v[174:177], v[224:227], v[66:69]
	s_setprio 0
	s_barrier
	s_add_i32 s93, s93, s23
	v_lshl_add_u64 v[140:141], s[76:77], 0, v[0:1]
	s_mov_b32 m0, s93
	ds_read_b128 v[178:181], v145 offset:16384
	ds_read_b128 v[182:185], v241 offset:16384
	ds_read_b128 v[190:193], v145 offset:18432
	ds_read_b128 v[194:197], v241 offset:18432
	ds_read_b128 v[198:201], v145 offset:20480
	ds_read_b128 v[216:219], v241 offset:20480
	ds_read_b128 v[220:223], v145 offset:22528
	ds_read_b128 v[224:227], v241 offset:22528
	global_load_lds_dwordx4 v[140:141], off
	s_add_i32 m0, s93, 0x2000
	s_add_u32 s98, s76, 0x80000
	v_lshl_add_u64 v[202:203], s[76:77], 0, v[134:135]
	s_addc_u32 s99, s77, 0
	s_add_i32 s75, s75, s23
	global_load_lds_dwordx4 v[202:203], off
	v_lshl_add_u64 v[228:229], s[98:99], 0, v[0:1]
	s_mov_b32 m0, s75
	v_lshl_add_u64 v[230:231], vcc, 0, v[132:133]
	global_load_lds_dwordx4 v[228:229], off
	v_lshl_add_u64 v[228:229], s[98:99], 0, v[134:135]
	s_add_i32 m0, s75, 0x2000
	s_nop 0
	global_load_lds_dwordx4 v[228:229], off
	v_lshl_add_u64 v[228:229], vcc, 0, v[130:131]
	s_mov_b32 m0, s81
	s_nop 0
	global_load_lds_dwordx4 v[228:229], off
	s_mov_b32 m0, s60
	s_nop 0
	global_load_lds_dwordx4 v[230:231], off
	s_waitcnt vmcnt(8)
	s_waitcnt lgkmcnt(0)
	s_barrier
	s_setprio 1
	s_waitcnt lgkmcnt(0)
	v_mfma_f32_16x16x32_bf16 v[62:65], v[146:149], v[178:181], v[62:65]
	v_mfma_f32_16x16x32_bf16 v[58:61], v[154:157], v[178:181], v[58:61]
	v_mfma_f32_16x16x32_bf16 v[46:49], v[146:149], v[190:193], v[46:49]
	v_mfma_f32_16x16x32_bf16 v[42:45], v[154:157], v[190:193], v[42:45]
	v_mfma_f32_16x16x32_bf16 v[30:33], v[146:149], v[198:201], v[30:33]
	v_mfma_f32_16x16x32_bf16 v[26:29], v[154:157], v[198:201], v[26:29]
	v_mfma_f32_16x16x32_bf16 v[14:17], v[146:149], v[220:223], v[14:17]
	v_mfma_f32_16x16x32_bf16 v[10:13], v[154:157], v[220:223], v[10:13]
	v_mfma_f32_16x16x32_bf16 v[62:65], v[150:153], v[182:185], v[62:65]
	v_mfma_f32_16x16x32_bf16 v[58:61], v[158:161], v[182:185], v[58:61]
	v_mfma_f32_16x16x32_bf16 v[46:49], v[150:153], v[194:197], v[46:49]
	v_mfma_f32_16x16x32_bf16 v[42:45], v[158:161], v[194:197], v[42:45]
	v_mfma_f32_16x16x32_bf16 v[30:33], v[150:153], v[216:219], v[30:33]
	v_mfma_f32_16x16x32_bf16 v[26:29], v[158:161], v[216:219], v[26:29]
	v_mfma_f32_16x16x32_bf16 v[14:17], v[150:153], v[224:227], v[14:17]
	v_mfma_f32_16x16x32_bf16 v[10:13], v[158:161], v[224:227], v[10:13]
	s_setprio 0
	s_setprio 1
	v_mfma_f32_16x16x32_bf16 v[54:57], v[162:165], v[178:181], v[54:57]
	v_mfma_f32_16x16x32_bf16 v[50:53], v[170:173], v[178:181], v[50:53]
	v_mfma_f32_16x16x32_bf16 v[38:41], v[162:165], v[190:193], v[38:41]
	v_mfma_f32_16x16x32_bf16 v[34:37], v[170:173], v[190:193], v[34:37]
	v_mfma_f32_16x16x32_bf16 v[22:25], v[162:165], v[198:201], v[22:25]
	v_mfma_f32_16x16x32_bf16 v[18:21], v[170:173], v[198:201], v[18:21]
	v_mfma_f32_16x16x32_bf16 v[6:9], v[162:165], v[220:223], v[6:9]
	v_mfma_f32_16x16x32_bf16 v[2:5], v[170:173], v[220:223], v[2:5]
	v_mfma_f32_16x16x32_bf16 v[54:57], v[166:169], v[182:185], v[54:57]
	v_mfma_f32_16x16x32_bf16 v[50:53], v[174:177], v[182:185], v[50:53]
	v_mfma_f32_16x16x32_bf16 v[38:41], v[166:169], v[194:197], v[38:41]
	v_mfma_f32_16x16x32_bf16 v[34:37], v[174:177], v[194:197], v[34:37]
	v_mfma_f32_16x16x32_bf16 v[22:25], v[166:169], v[216:219], v[22:25]
	v_mfma_f32_16x16x32_bf16 v[18:21], v[174:177], v[216:219], v[18:21]
	v_mfma_f32_16x16x32_bf16 v[6:9], v[166:169], v[224:227], v[6:9]
	v_mfma_f32_16x16x32_bf16 v[2:5], v[174:177], v[224:227], v[2:5]
	s_setprio 0
	s_barrier
	s_add_i32 s75, 0, 0x18000
	s_add_i32 s93, 0, 0x1c000
	v_add_u32_e32 v158, s75, v143
	v_add_u32_e32 v242, s75, v240
	v_add_u32_e32 v174, s93, v143
	v_add_u32_e32 v243, s93, v240
	ds_read_b128 v[146:149], v158
	ds_read_b128 v[150:153], v242
	ds_read_b128 v[154:157], v158 offset:2048
	ds_read_b128 v[158:161], v242 offset:2048
	ds_read_b128 v[162:165], v174
	ds_read_b128 v[166:169], v243
	ds_read_b128 v[170:173], v174 offset:2048
	ds_read_b128 v[174:177], v243 offset:2048
	s_add_u32 s98, vcc_lo, 0x80000
	s_addc_u32 s99, vcc_hi, 0
	s_mov_b32 m0, s61
	v_lshl_add_u64 v[232:233], s[98:99], 0, v[130:131]
	ds_read_b128 v[178:181], v145 offset:32768
	ds_read_b128 v[182:185], v241 offset:32768
	ds_read_b128 v[190:193], v145 offset:34816
	ds_read_b128 v[194:197], v241 offset:34816
	ds_read_b128 v[198:201], v145 offset:36864
	ds_read_b128 v[216:219], v241 offset:36864
	ds_read_b128 v[220:223], v145 offset:38912
	ds_read_b128 v[224:227], v241 offset:38912
	global_load_lds_dwordx4 v[232:233], off
	v_lshl_add_u64 v[232:233], s[98:99], 0, v[132:133]
	s_mov_b32 m0, s64
	s_nop 0
	global_load_lds_dwordx4 v[232:233], off
	s_waitcnt vmcnt(8)
	s_waitcnt lgkmcnt(0)
	s_barrier
	s_setprio 1
	s_waitcnt lgkmcnt(0)
	v_mfma_f32_16x16x32_bf16 v[126:129], v[146:149], v[178:181], v[126:129]
	v_mfma_f32_16x16x32_bf16 v[122:125], v[154:157], v[178:181], v[122:125]
	v_mfma_f32_16x16x32_bf16 v[114:117], v[146:149], v[190:193], v[114:117]
	v_mfma_f32_16x16x32_bf16 v[106:109], v[154:157], v[190:193], v[106:109]
	v_mfma_f32_16x16x32_bf16 v[98:101], v[146:149], v[198:201], v[98:101]
	v_mfma_f32_16x16x32_bf16 v[90:93], v[154:157], v[198:201], v[90:93]
	v_mfma_f32_16x16x32_bf16 v[82:85], v[146:149], v[220:223], v[82:85]
	v_mfma_f32_16x16x32_bf16 v[74:77], v[154:157], v[220:223], v[74:77]
	v_mfma_f32_16x16x32_bf16 v[126:129], v[150:153], v[182:185], v[126:129]
	v_mfma_f32_16x16x32_bf16 v[122:125], v[158:161], v[182:185], v[122:125]
	v_mfma_f32_16x16x32_bf16 v[114:117], v[150:153], v[194:197], v[114:117]
	v_mfma_f32_16x16x32_bf16 v[106:109], v[158:161], v[194:197], v[106:109]
	v_mfma_f32_16x16x32_bf16 v[98:101], v[150:153], v[216:219], v[98:101]
	v_mfma_f32_16x16x32_bf16 v[90:93], v[158:161], v[216:219], v[90:93]
	v_mfma_f32_16x16x32_bf16 v[82:85], v[150:153], v[224:227], v[82:85]
	v_mfma_f32_16x16x32_bf16 v[74:77], v[158:161], v[224:227], v[74:77]
	s_setprio 0
	s_setprio 1
	v_mfma_f32_16x16x32_bf16 v[118:121], v[162:165], v[178:181], v[118:121]
	v_mfma_f32_16x16x32_bf16 v[110:113], v[170:173], v[178:181], v[110:113]
	v_mfma_f32_16x16x32_bf16 v[102:105], v[162:165], v[190:193], v[102:105]
	v_mfma_f32_16x16x32_bf16 v[94:97], v[170:173], v[190:193], v[94:97]
	v_mfma_f32_16x16x32_bf16 v[86:89], v[162:165], v[198:201], v[86:89]
	v_mfma_f32_16x16x32_bf16 v[78:81], v[170:173], v[198:201], v[78:81]
	v_mfma_f32_16x16x32_bf16 v[70:73], v[162:165], v[220:223], v[70:73]
	v_mfma_f32_16x16x32_bf16 v[66:69], v[170:173], v[220:223], v[66:69]
	v_mfma_f32_16x16x32_bf16 v[118:121], v[166:169], v[182:185], v[118:121]
	v_mfma_f32_16x16x32_bf16 v[110:113], v[174:177], v[182:185], v[110:113]
	v_mfma_f32_16x16x32_bf16 v[102:105], v[166:169], v[194:197], v[102:105]
	v_mfma_f32_16x16x32_bf16 v[94:97], v[174:177], v[194:197], v[94:97]
	v_mfma_f32_16x16x32_bf16 v[86:89], v[166:169], v[216:219], v[86:89]
	v_mfma_f32_16x16x32_bf16 v[78:81], v[174:177], v[216:219], v[78:81]
	v_mfma_f32_16x16x32_bf16 v[70:73], v[166:169], v[224:227], v[70:73]
	v_mfma_f32_16x16x32_bf16 v[66:69], v[174:177], v[224:227], v[66:69]
	s_setprio 0
	s_barrier
	s_add_i32 s75, s75, s23
	v_lshl_add_u64 v[140:141], v[140:141], 0, s[20:21]
	s_mov_b32 m0, s75
	ds_read_b128 v[178:181], v145 offset:49152
	ds_read_b128 v[182:185], v241 offset:49152
	ds_read_b128 v[190:193], v145 offset:51200
	ds_read_b128 v[194:197], v241 offset:51200
	ds_read_b128 v[198:201], v145 offset:53248
	ds_read_b128 v[216:219], v241 offset:53248
	ds_read_b128 v[220:223], v145 offset:55296
	ds_read_b128 v[224:227], v241 offset:55296
	global_load_lds_dwordx4 v[140:141], off
	s_add_i32 m0, s75, 0x2000
	s_add_u32 s76, s76, 0x80080
	v_lshl_add_u64 v[140:141], v[202:203], 0, s[20:21]
	s_addc_u32 s77, s77, 0
	s_add_i32 s75, s93, s23
	global_load_lds_dwordx4 v[140:141], off
	v_lshl_add_u64 v[140:141], s[76:77], 0, v[0:1]
	s_mov_b32 m0, s75
	s_nop 0
	global_load_lds_dwordx4 v[140:141], off
	v_lshl_add_u64 v[140:141], s[76:77], 0, v[134:135]
	s_add_i32 m0, s75, 0x2000
	s_nop 0
	global_load_lds_dwordx4 v[140:141], off
	v_lshl_add_u64 v[140:141], v[228:229], 0, s[20:21]
	s_mov_b32 m0, s65
	s_nop 0
	global_load_lds_dwordx4 v[140:141], off
	v_lshl_add_u64 v[140:141], v[230:231], 0, s[20:21]
	s_mov_b32 m0, s66
	s_nop 0
	global_load_lds_dwordx4 v[140:141], off
	s_waitcnt vmcnt(8)
	s_waitcnt lgkmcnt(0)
	s_barrier
	s_setprio 1
	s_waitcnt lgkmcnt(0)
	v_mfma_f32_16x16x32_bf16 v[62:65], v[146:149], v[178:181], v[62:65]
	v_mfma_f32_16x16x32_bf16 v[58:61], v[154:157], v[178:181], v[58:61]
	v_mfma_f32_16x16x32_bf16 v[46:49], v[146:149], v[190:193], v[46:49]
	v_mfma_f32_16x16x32_bf16 v[42:45], v[154:157], v[190:193], v[42:45]
	v_mfma_f32_16x16x32_bf16 v[30:33], v[146:149], v[198:201], v[30:33]
	v_mfma_f32_16x16x32_bf16 v[26:29], v[154:157], v[198:201], v[26:29]
	v_mfma_f32_16x16x32_bf16 v[14:17], v[146:149], v[220:223], v[14:17]
	v_mfma_f32_16x16x32_bf16 v[10:13], v[154:157], v[220:223], v[10:13]
	v_mfma_f32_16x16x32_bf16 v[62:65], v[150:153], v[182:185], v[62:65]
	v_mfma_f32_16x16x32_bf16 v[58:61], v[158:161], v[182:185], v[58:61]
	v_mfma_f32_16x16x32_bf16 v[46:49], v[150:153], v[194:197], v[46:49]
	v_mfma_f32_16x16x32_bf16 v[42:45], v[158:161], v[194:197], v[42:45]
	v_mfma_f32_16x16x32_bf16 v[30:33], v[150:153], v[216:219], v[30:33]
	v_mfma_f32_16x16x32_bf16 v[26:29], v[158:161], v[216:219], v[26:29]
	v_mfma_f32_16x16x32_bf16 v[14:17], v[150:153], v[224:227], v[14:17]
	v_mfma_f32_16x16x32_bf16 v[10:13], v[158:161], v[224:227], v[10:13]
	s_setprio 0
	s_setprio 1
	v_mfma_f32_16x16x32_bf16 v[54:57], v[162:165], v[178:181], v[54:57]
	v_mfma_f32_16x16x32_bf16 v[50:53], v[170:173], v[178:181], v[50:53]
	v_mfma_f32_16x16x32_bf16 v[38:41], v[162:165], v[190:193], v[38:41]
	v_mfma_f32_16x16x32_bf16 v[34:37], v[170:173], v[190:193], v[34:37]
	v_mfma_f32_16x16x32_bf16 v[22:25], v[162:165], v[198:201], v[22:25]
	v_mfma_f32_16x16x32_bf16 v[18:21], v[170:173], v[198:201], v[18:21]
	v_mfma_f32_16x16x32_bf16 v[6:9], v[162:165], v[220:223], v[6:9]
	v_mfma_f32_16x16x32_bf16 v[2:5], v[170:173], v[220:223], v[2:5]
	v_mfma_f32_16x16x32_bf16 v[54:57], v[166:169], v[182:185], v[54:57]
	v_mfma_f32_16x16x32_bf16 v[50:53], v[174:177], v[182:185], v[50:53]
	v_mfma_f32_16x16x32_bf16 v[38:41], v[166:169], v[194:197], v[38:41]
	v_mfma_f32_16x16x32_bf16 v[34:37], v[174:177], v[194:197], v[34:37]
	v_mfma_f32_16x16x32_bf16 v[22:25], v[166:169], v[216:219], v[22:25]
	v_mfma_f32_16x16x32_bf16 v[18:21], v[174:177], v[216:219], v[18:21]
	v_mfma_f32_16x16x32_bf16 v[6:9], v[166:169], v[224:227], v[6:9]
	v_mfma_f32_16x16x32_bf16 v[2:5], v[174:177], v[224:227], v[2:5]
	s_setprio 0
	s_barrier
	s_add_i32 s74, s74, 2
	s_add_u32 s72, s72, 0x100
	s_addc_u32 s73, s73, 0
	s_add_u32 s82, s82, 0x100
	s_addc_u32 s83, s83, 0
	s_cmp_gt_u32 s74, 29
	s_cbranch_scc0 .LBB0_469
	s_and_b64 vcc, exec, s[94:95]
	s_cbranch_vccz .LBB0_472
	s_barrier

	.amdhsa_kernel _Z4mega6Params
		.amdhsa_group_segment_fixed_size 0
		.amdhsa_private_segment_fixed_size 0
		.amdhsa_kernarg_size 368
		.amdhsa_user_sgpr_count 2
		.amdhsa_user_sgpr_dispatch_ptr 0
		.amdhsa_user_sgpr_queue_ptr 0
		.amdhsa_user_sgpr_kernarg_segment_ptr 1
		.amdhsa_user_sgpr_dispatch_id 0
		.amdhsa_user_sgpr_kernarg_preload_length 0
		.amdhsa_user_sgpr_kernarg_preload_offset 0
		.amdhsa_user_sgpr_private_segment_size 0
		.amdhsa_uses_dynamic_stack 0
		.amdhsa_enable_private_segment 0
		.amdhsa_system_sgpr_workgroup_id_x 1
		.amdhsa_system_sgpr_workgroup_id_y 0
		.amdhsa_system_sgpr_workgroup_id_z 0
		.amdhsa_system_sgpr_workgroup_info 0
		.amdhsa_system_vgpr_workitem_id 2
		.amdhsa_next_free_vgpr 252
		.amdhsa_next_free_sgpr 100
		.amdhsa_accum_offset 252
		.amdhsa_reserve_vcc 1
		.amdhsa_float_round_mode_32 0
		.amdhsa_float_round_mode_16_64 0
		.amdhsa_float_denorm_mode_32 3
		.amdhsa_float_denorm_mode_16_64 3
		.amdhsa_dx10_clamp 1
		.amdhsa_ieee_mode 1
		.amdhsa_fp16_overflow 0
		.amdhsa_tg_split 0
		.amdhsa_exception_fp_ieee_invalid_op 0
		.amdhsa_exception_fp_denorm_src 0
		.amdhsa_exception_fp_ieee_div_zero 0
		.amdhsa_exception_fp_ieee_overflow 0
		.amdhsa_exception_fp_ieee_underflow 0
		.amdhsa_exception_fp_ieee_inexact 0
		.amdhsa_exception_int_div_zero 0
	.end_amdhsa_kernel

amdhsa.kernels:
  - .agpr_count:     0
    .args:
      - .offset:         0
        .size:           112
        .value_kind:     by_value
      - .offset:         112
        .size:           4
        .value_kind:     hidden_block_count_x
      - .offset:         116
        .size:           4
        .value_kind:     hidden_block_count_y
      - .offset:         120
        .size:           4
        .value_kind:     hidden_block_count_z
      - .offset:         124
        .size:           2
        .value_kind:     hidden_group_size_x
      - .offset:         126
        .size:           2
        .value_kind:     hidden_group_size_y
      - .offset:         128
        .size:           2
        .value_kind:     hidden_group_size_z
      - .offset:         130
        .size:           2
        .value_kind:     hidden_remainder_x
      - .offset:         132
        .size:           2
        .value_kind:     hidden_remainder_y
      - .offset:         134
        .size:           2
        .value_kind:     hidden_remainder_z
      - .offset:         152
        .size:           8
        .value_kind:     hidden_global_offset_x
      - .offset:         160
        .size:           8
        .value_kind:     hidden_global_offset_y
      - .offset:         168
        .size:           8
        .value_kind:     hidden_global_offset_z
      - .offset:         176
        .size:           2
        .value_kind:     hidden_grid_dims
      - .offset:         200
        .size:           8
        .value_kind:     hidden_multigrid_sync_arg
      - .offset:         232
        .size:           4
        .value_kind:     hidden_dynamic_lds_size
    .group_segment_fixed_size: 0
    .kernarg_segment_align: 8
    .kernarg_segment_size: 368
    .language:       OpenCL C
    .language_version:
      - 2
      - 0
    .max_flat_workgroup_size: 512
    .name:           _Z4mega6Params
    .private_segment_fixed_size: 0
    .sgpr_count:     106
    .sgpr_spill_count: 176
    .symbol:         _Z4mega6Params.kd
    .uniform_work_group_size: 1
    .uses_dynamic_stack: false
    .vgpr_count:     252
    .vgpr_spill_count: 0
    .wavefront_size: 64
